# GEMM tails: small tiles dealt over all 256 workgroups (nx=1) instead of per XCD group
# baseline (speedup 1.0000x reference)
; #define LAS __attribute__((address_space(3)))
; #define TAIL_PF(ap_, bp_) do { _Pragma("unroll") for (int s_ = 0; s_ < 4; ++s_) { _Pragma("unroll") for (int i = 0; i < 2; ++i) pa[s_][i] = *(const bf16x8*)((ap_) + i * a16 + 32 * s_); \
;         _Pragma("unroll") for (int f = 0; f < 4; ++f) pb[s_][f] = *(const bf16x8*)((bp_) + f * b16 + 32 * s_); } } while (0)
; template <class Epi>
; __device__ __forceinline__ void gemm_tail(LAS unsigned char* lds_in, int wave_in, const Gemm g, const Epi& E) {
;     ...
;     int G = gridDim.x, bid = blockIdx.x; asm volatile("" : "+s"(G)); asm volatile("" : "+s"(bid));
;     const int r = lane & 15, q = lane >> 4;
;     constexpr int NRT = (MREAL - MTAIL0) / 32, NCT = 1024 / 64;
;     const int klen = g.K / 8, kbeg = wid * klen;
;     const int nx = (G % 8 == 0) ? 8 : 1, x = (nx == 8) ? (bid & 7) : 0, j = (nx == 8) ? (bid >> 3) : bid, nj = G / nx;
;     const int ct_per = NCT / nx, ntile = NRT * ct_per;
;     LAS float* red = (LAS float*)lds;
;     const size_t a16 = (size_t)16 * g.lda, b16 = (size_t)16 * g.ldb;
;     bf16x8 pa[4][2], pb[4][4];
;     ...
;     if (j < ntile) { TAIL_PTRS(j, rt0, ct0, row00, col00, ap0, bp0); (void)row00; TAIL_PF(ap0, bp0); }
.LBB0_840:
	v_mov_b32_e32 v98, v174
	s_mov_b32 s15, s75
	s_mov_b32 s14, s77
	s_mov_b32 s12, s74
	s_mov_b32 s13, s70
	s_and_b32 s0, s12, 7
	s_ashr_i32 s16, s13, 3
	s_cmp_eq_u32 s0, 8
	s_cselect_b64 s[2:3], -1, 0
	s_and_b64 s[0:1], s[2:3], exec
	s_movk_i32 s1, 0x48
	s_cselect_b32 s0, s16, s13
	s_cselect_b32 s1, s1, 0x240
	s_cmp_ge_i32 s0, s1
	s_cbranch_scc1 .LBB0_845
	s_and_b64 s[16:17], s[2:3], exec
	s_cselect_b32 s16, 8, 1
	v_cvt_f32_ubyte0_e32 v1, s16
	v_rcp_iflag_f32_e32 v2, v1
	s_sub_i32 s18, 0, s16
	s_ashr_i32 s17, s12, 31
	s_abs_i32 s12, s12
	v_mul_f32_e32 v2, 0x4f7ffffe, v2
	v_cvt_u32_f32_e32 v2, v2
	v_and_b32_e32 v1, 15, v98
	v_ashrrev_i32_e32 v99, 4, v98
	v_mov_b32_e32 v3, v0
	v_readfirstlane_b32 s19, v2
	s_mul_i32 s18, s18, s19
	s_mul_hi_u32 s18, s19, s18
	s_add_i32 s19, s19, s18
	s_mul_hi_u32 s18, s12, s19
	s_mul_i32 s19, s18, s16
	s_sub_i32 s12, s12, s19
	s_add_i32 s20, s18, 1
	s_sub_i32 s19, s12, s16
	s_cmp_ge_u32 s12, s16
	s_cselect_b32 s18, s20, s18
	s_cselect_b32 s12, s19, s12
	s_add_i32 s19, s18, 1
	s_cmp_ge_u32 s12, s16
	s_cselect_b32 s12, s19, s18
	s_xor_b32 s12, s12, s17
	s_sub_i32 s12, s12, s17
	s_and_b32 s13, s13, 7
	s_and_b64 s[16:17], s[2:3], exec
	s_mul_hi_i32 s17, s0, 0x38e38e39
	s_cselect_b32 s13, s13, 0
	s_lshr_b32 s18, s17, 31
	s_ashr_i32 s17, s17, 3
	s_add_i32 s17, s17, s18
	s_mul_i32 s18, s17, 36
	s_lshl_b32 s16, s15, 7
	s_sub_i32 s18, s0, s18
	s_and_b64 s[2:3], s[2:3], exec
	s_cselect_b32 s2, 1, 4
	s_lshl_b32 s13, s13, s2
	s_lshl_b32 s2, s18, 5
	s_addk_i32 s2, 0x4000
	v_or_b32_e32 v2, s2, v1
	v_lshlrev_b32_e32 v4, 3, v99
	v_lshlrev_b64 v[2:3], 11, v[2:3]
	v_ashrrev_i32_e32 v5, 31, v4
	s_add_i32 s19, s13, s17
	v_lshl_add_u64 v[2:3], s[8:9], 0, v[2:3]
	v_lshlrev_b64 v[100:101], 1, v[4:5]
	s_ashr_i32 s17, s16, 31
	v_lshl_add_u64 v[2:3], v[2:3], 0, v[100:101]
	s_lshl_b64 s[2:3], s[16:17], 1
	v_lshl_add_u64 v[54:55], v[2:3], 0, s[2:3]
	v_lshl_or_b32 v2, s19, 6, v1
	v_ashrrev_i32_e32 v3, 31, v2
	v_lshlrev_b64 v[2:3], 11, v[2:3]
	v_lshl_add_u64 v[2:3], s[10:11], 0, v[2:3]
	v_lshl_add_u64 v[2:3], v[2:3], 0, v[100:101]
	v_add_co_u32_e32 v62, vcc, s29, v54
	v_lshl_add_u64 v[70:71], v[2:3], 0, s[2:3]
	s_nop 0
	v_addc_co_u32_e32 v63, vcc, 0, v55, vcc
	v_add_co_u32_e32 v78, vcc, s29, v70
	v_lshl_add_u64 v[102:103], s[8:9], 0, v[100:101]
	s_nop 0
	v_addc_co_u32_e32 v79, vcc, 0, v71, vcc
	v_add_co_u32_e32 v86, vcc, s50, v70
	v_lshl_add_u64 v[100:101], s[10:11], 0, v[100:101]
	s_nop 0
	v_addc_co_u32_e32 v87, vcc, 0, v71, vcc
	v_add_co_u32_e32 v94, vcc, s51, v70
	v_lshl_add_u64 v[130:131], v[102:103], 0, s[2:3]
	s_nop 0
	v_addc_co_u32_e32 v95, vcc, 0, v71, vcc
	global_load_dwordx4 v[2:5], v[54:55], off
	global_load_dwordx4 v[6:9], v[54:55], off offset:64
	global_load_dwordx4 v[10:13], v[62:63], off
	global_load_dwordx4 v[14:17], v[62:63], off offset:64
	global_load_dwordx4 v[18:21], v[70:71], off
	global_load_dwordx4 v[22:25], v[70:71], off offset:64
	global_load_dwordx4 v[26:29], v[78:79], off
	global_load_dwordx4 v[30:33], v[78:79], off offset:64
	global_load_dwordx4 v[34:37], v[86:87], off
	global_load_dwordx4 v[38:41], v[86:87], off offset:64
	global_load_dwordx4 v[42:45], v[94:95], off
	global_load_dwordx4 v[46:49], v[94:95], off offset:64
	global_load_dwordx4 v[50:53], v[54:55], off offset:128
	s_nop 0
	global_load_dwordx4 v[54:57], v[54:55], off offset:192
	s_nop 0
	global_load_dwordx4 v[58:61], v[62:63], off offset:128
	s_nop 0
	global_load_dwordx4 v[62:65], v[62:63], off offset:192
	s_nop 0
	global_load_dwordx4 v[66:69], v[70:71], off offset:128
	s_nop 0
	global_load_dwordx4 v[70:73], v[70:71], off offset:192
	s_nop 0
	global_load_dwordx4 v[74:77], v[78:79], off offset:128
	s_nop 0
	global_load_dwordx4 v[78:81], v[78:79], off offset:192
	s_nop 0
	global_load_dwordx4 v[82:85], v[86:87], off offset:128
	s_nop 0
	global_load_dwordx4 v[86:89], v[86:87], off offset:192
	s_nop 0
	global_load_dwordx4 v[90:93], v[94:95], off offset:128
	s_nop 0
	global_load_dwordx4 v[94:97], v[94:95], off offset:192
	v_lshl_add_u64 v[132:133], v[100:101], 0, s[2:3]
	s_lshl_b32 s2, s15, 13
	v_lshl_add_u32 v99, s15, 2, v99
	s_add_i32 s2, s14, s2
	s_lshl_b32 s9, s12, 5
	v_lshl_add_u32 v100, v1, 8, s2
	v_and_b32_e32 v98, -16, v98
	v_lshlrev_b32_e32 v101, 8, v99
	v_lshlrev_b32_e32 v102, 4, v1
	s_add_i32 s2, s9, 0x4000
	v_lshlrev_b32_e32 v140, 2, v1
	v_add3_u32 v141, s14, v101, v102
	v_add_u32_e32 v142, 0x4000, v99
	s_lshl_b32 s8, s0, 5
	v_or_b32_e32 v143, s2, v1
	v_add_u32_e32 v144, v100, v98
	s_branch .LBB0_843

; #define LAS __attribute__((address_space(3)))
; #define TAIL_PF(ap_, bp_) do { _Pragma("unroll") for (int s_ = 0; s_ < 4; ++s_) { _Pragma("unroll") for (int i = 0; i < 2; ++i) pa[s_][i] = *(const bf16x8*)((ap_) + i * a16 + 32 * s_); \
;         _Pragma("unroll") for (int f = 0; f < 4; ++f) pb[s_][f] = *(const bf16x8*)((bp_) + f * b16 + 32 * s_); } } while (0)
; template <class Epi>
; __device__ __forceinline__ void gemm_tail(LAS unsigned char* lds_in, int wave_in, const Gemm g, const Epi& E) {
;     ...
;     int G = gridDim.x, bid = blockIdx.x; asm volatile("" : "+s"(G)); asm volatile("" : "+s"(bid));
;     const int r = lane & 15, q = lane >> 4;
;     constexpr int NRT = (MREAL - MTAIL0) / 32, NCT = 1024 / 64;
;     const int klen = g.K / 8, kbeg = wid * klen;
;     const int nx = (G % 8 == 0) ? 8 : 1, x = (nx == 8) ? (bid & 7) : 0, j = (nx == 8) ? (bid >> 3) : bid, nj = G / nx;
;     const int ct_per = NCT / nx, ntile = NRT * ct_per;
;     LAS float* red = (LAS float*)lds;
;     const size_t a16 = (size_t)16 * g.lda, b16 = (size_t)16 * g.ldb;
;     bf16x8 pa[4][2], pb[4][4];
;     ...
;     if (j < ntile) { TAIL_PTRS(j, rt0, ct0, row00, col00, ap0, bp0); (void)row00; TAIL_PF(ap0, bp0); }
.LBB0_921:
	v_mov_b32_e32 v98, v174
	s_mov_b32 s18, s75
	s_mov_b32 s17, s77
	s_mov_b32 s14, s74
	s_mov_b32 s15, s70
	s_and_b32 s0, s14, 7
	s_ashr_i32 s16, s15, 3
	s_cmp_eq_u32 s0, 8
	s_cselect_b64 s[2:3], -1, 0
	s_and_b64 s[0:1], s[2:3], exec
	s_movk_i32 s1, 0x48
	s_cselect_b32 s0, s16, s15
	s_cselect_b32 s1, s1, 0x240
	s_cmp_ge_i32 s0, s1
	s_cbranch_scc1 .LBB0_926
	s_and_b64 s[20:21], s[2:3], exec
	s_cselect_b32 s16, 8, 1
	v_cvt_f32_ubyte0_e32 v1, s16
	v_rcp_iflag_f32_e32 v2, v1
	s_sub_i32 s20, 0, s16
	s_ashr_i32 s19, s14, 31
	s_abs_i32 s14, s14
	v_mul_f32_e32 v2, 0x4f7ffffe, v2
	v_cvt_u32_f32_e32 v2, v2
	v_and_b32_e32 v1, 15, v98
	v_ashrrev_i32_e32 v99, 4, v98
	v_mov_b32_e32 v3, v0
	v_readfirstlane_b32 s21, v2
	s_mul_i32 s20, s20, s21
	s_mul_hi_u32 s20, s21, s20
	s_add_i32 s21, s21, s20
	s_mul_hi_u32 s20, s14, s21
	s_mul_i32 s21, s20, s16
	s_sub_i32 s14, s14, s21
	s_add_i32 s22, s20, 1
	s_sub_i32 s21, s14, s16
	s_cmp_ge_u32 s14, s16
	s_cselect_b32 s20, s22, s20
	s_cselect_b32 s14, s21, s14
	s_add_i32 s21, s20, 1
	s_cmp_ge_u32 s14, s16
	s_cselect_b32 s14, s21, s20
	s_xor_b32 s14, s14, s19
	s_sub_i32 s14, s14, s19
	s_and_b32 s15, s15, 7
	s_and_b64 s[20:21], s[2:3], exec
	s_mul_hi_i32 s16, s0, 0x38e38e39
	s_cselect_b32 s15, s15, 0
	s_lshr_b32 s19, s16, 31
	s_ashr_i32 s16, s16, 3
	s_add_i32 s16, s16, s19
	s_mul_i32 s19, s16, 36
	s_lshl_b32 s20, s18, 8
	s_sub_i32 s19, s0, s19
	s_and_b64 s[2:3], s[2:3], exec
	s_cselect_b32 s2, 1, 4
	s_lshl_b32 s15, s15, s2
	s_lshl_b32 s2, s19, 5
	s_addk_i32 s2, 0x4000
	v_or_b32_e32 v2, s2, v1
	v_lshlrev_b32_e32 v4, 3, v99
	v_lshlrev_b64 v[2:3], 12, v[2:3]
	v_ashrrev_i32_e32 v5, 31, v4
	v_lshl_add_u64 v[2:3], s[10:11], 0, v[2:3]
	v_lshlrev_b64 v[100:101], 1, v[4:5]
	s_ashr_i32 s21, s20, 31
	s_add_i32 s16, s15, s16
	v_lshl_add_u64 v[2:3], v[2:3], 0, v[100:101]
	s_lshl_b64 s[2:3], s[20:21], 1
	v_lshl_add_u64 v[54:55], v[2:3], 0, s[2:3]
	v_lshl_or_b32 v2, s16, 6, v1
	v_ashrrev_i32_e32 v3, 31, v2
	v_lshlrev_b64 v[2:3], 12, v[2:3]
	v_lshl_add_u64 v[2:3], s[12:13], 0, v[2:3]
	v_lshl_add_u64 v[2:3], v[2:3], 0, v[100:101]
	v_add_co_u32_e32 v62, vcc, s50, v54
	v_lshl_add_u64 v[70:71], v[2:3], 0, s[2:3]
	s_nop 0
	v_addc_co_u32_e32 v63, vcc, 0, v55, vcc
	v_add_co_u32_e32 v78, vcc, s50, v70
	v_lshl_add_u64 v[102:103], s[10:11], 0, v[100:101]
	s_nop 0
	v_addc_co_u32_e32 v79, vcc, 0, v71, vcc
	v_add_co_u32_e32 v86, vcc, s49, v70
	v_lshl_add_u64 v[100:101], s[12:13], 0, v[100:101]
	s_nop 0
	v_addc_co_u32_e32 v87, vcc, 0, v71, vcc
	v_add_co_u32_e32 v94, vcc, s48, v70
	v_lshl_add_u64 v[130:131], v[102:103], 0, s[2:3]
	s_nop 0
	v_addc_co_u32_e32 v95, vcc, 0, v71, vcc
	global_load_dwordx4 v[2:5], v[54:55], off
	global_load_dwordx4 v[6:9], v[54:55], off offset:64
	global_load_dwordx4 v[10:13], v[62:63], off
	global_load_dwordx4 v[14:17], v[62:63], off offset:64
	global_load_dwordx4 v[18:21], v[70:71], off
	global_load_dwordx4 v[22:25], v[70:71], off offset:64
	global_load_dwordx4 v[26:29], v[78:79], off
	global_load_dwordx4 v[30:33], v[78:79], off offset:64
	global_load_dwordx4 v[34:37], v[86:87], off
	global_load_dwordx4 v[38:41], v[86:87], off offset:64
	global_load_dwordx4 v[42:45], v[94:95], off
	global_load_dwordx4 v[46:49], v[94:95], off offset:64
	global_load_dwordx4 v[50:53], v[54:55], off offset:128
	s_nop 0
	global_load_dwordx4 v[54:57], v[54:55], off offset:192
	s_nop 0
	global_load_dwordx4 v[58:61], v[62:63], off offset:128
	s_nop 0
	global_load_dwordx4 v[62:65], v[62:63], off offset:192
	s_nop 0
	global_load_dwordx4 v[66:69], v[70:71], off offset:128
	s_nop 0
	global_load_dwordx4 v[70:73], v[70:71], off offset:192
	s_nop 0
	global_load_dwordx4 v[74:77], v[78:79], off offset:128
	s_nop 0
	global_load_dwordx4 v[78:81], v[78:79], off offset:192
	s_nop 0
	global_load_dwordx4 v[82:85], v[86:87], off offset:128
	s_nop 0
	global_load_dwordx4 v[86:89], v[86:87], off offset:192
	s_nop 0
	global_load_dwordx4 v[90:93], v[94:95], off offset:128
	s_nop 0
	global_load_dwordx4 v[94:97], v[94:95], off offset:192
	v_lshl_add_u64 v[132:133], v[100:101], 0, s[2:3]
	s_lshl_b32 s3, s18, 13
	s_add_i32 s3, s17, s3
	s_lshl_b32 s2, s18, 2
	v_lshl_add_u32 v100, v1, 8, s3
	s_lshl_b32 s3, s0, 5
	v_add_lshl_u32 v101, s2, v99, 8
	s_add_i32 s2, s2, s3
	s_addk_i32 s3, 0x4000
	v_and_b32_e32 v98, -16, v98
	v_lshlrev_b32_e32 v102, 4, v1
	v_add_u32_e32 v99, s2, v99
	s_lshl_b32 s10, s14, 5
	v_or_b32_e32 v143, s3, v1
	s_mov_b32 s16, 0
	v_lshlrev_b32_e32 v140, 2, v1
	v_add3_u32 v141, s17, v101, v102
	v_add_u32_e32 v142, 0x4000, v99
	v_add_u32_e32 v144, s10, v143
	v_add_u32_e32 v145, v100, v98
	s_branch .LBB0_924

; #define LAS __attribute__((address_space(3)))
; __device__ __forceinline__ float shx(float v, int m, int lane) { return __builtin_bit_cast(float, __builtin_amdgcn_ds_bpermute((lane ^ m) << 2, __builtin_bit_cast(int, v))); }
; #define TAIL_PF(ap_, bp_) do { _Pragma("unroll") for (int s_ = 0; s_ < 4; ++s_) { _Pragma("unroll") for (int i = 0; i < 2; ++i) pa[s_][i] = *(const bf16x8*)((ap_) + i * a16 + 32 * s_); \
;         _Pragma("unroll") for (int f = 0; f < 4; ++f) pb[s_][f] = *(const bf16x8*)((bp_) + f * b16 + 32 * s_); } } while (0)
;     __device__ __forceinline__ void tail4(const f32x4 v, const Pre& pre, int row, int col, int l16) const {
;     ...
;         ss += shx(ss, 1, l16); ss += shx(ss, 2, l16); ss += shx(ss, 4, l16); ss += shx(ss, 8, l16);
;         if ((l16 & 15) == 0) rss[(size_t)row * 16 + (col >> 6)] = ss;
; template <class Epi>
; __device__ __forceinline__ void gemm_tail(LAS unsigned char* lds_in, int wave_in, const Gemm g, const Epi& E) {
;     ...
;     int G = gridDim.x, bid = blockIdx.x; asm volatile("" : "+s"(G)); asm volatile("" : "+s"(bid));
;     const int r = lane & 15, q = lane >> 4;
;     constexpr int NRT = (MREAL - MTAIL0) / 32, NCT = 1024 / 64;
;     const int klen = g.K / 8, kbeg = wid * klen;
;     const int nx = (G % 8 == 0) ? 8 : 1, x = (nx == 8) ? (bid & 7) : 0, j = (nx == 8) ? (bid >> 3) : bid, nj = G / nx;
;     const int ct_per = NCT / nx, ntile = NRT * ct_per;
;     LAS float* red = (LAS float*)lds;
;     const size_t a16 = (size_t)16 * g.lda, b16 = (size_t)16 * g.ldb;
;     bf16x8 pa[4][2], pb[4][4];
;     ...
;     if (j < ntile) { TAIL_PTRS(j, rt0, ct0, row00, col00, ap0, bp0); (void)row00; TAIL_PF(ap0, bp0); }
.LBB0_1021:
	v_mov_b32_e32 v98, v174
	s_mov_b32 s5, s75
	s_mov_b32 s4, s77
	s_mov_b32 s16, s74
	s_mov_b32 s17, s70
	s_and_b32 s0, s16, 7
	s_ashr_i32 s18, s17, 3
	s_cmp_eq_u32 s0, 8
	s_cselect_b64 s[2:3], -1, 0
	s_and_b64 s[0:1], s[2:3], exec
	s_movk_i32 s1, 0x48
	s_cselect_b32 s0, s18, s17
	s_cselect_b32 s1, s1, 0x240
	s_cmp_ge_i32 s0, s1
	s_cbranch_scc1 .LBB0_1028
	s_and_b64 s[18:19], s[2:3], exec
	s_cselect_b32 s18, 8, 1
	v_cvt_f32_ubyte0_e32 v1, s18
	v_rcp_iflag_f32_e32 v2, v1
	s_sub_i32 s20, 0, s18
	s_ashr_i32 s19, s16, 31
	s_abs_i32 s16, s16
	v_mul_f32_e32 v2, 0x4f7ffffe, v2
	v_cvt_u32_f32_e32 v2, v2
	v_and_b32_e32 v1, 15, v98
	v_ashrrev_i32_e32 v99, 4, v98
	s_waitcnt lgkmcnt(0)
	v_mov_b32_e32 v3, v0
	v_readfirstlane_b32 s21, v2
	s_mul_i32 s20, s20, s21
	s_mul_hi_u32 s20, s21, s20
	s_add_i32 s21, s21, s20
	s_mul_hi_u32 s20, s16, s21
	s_mul_i32 s21, s20, s18
	s_sub_i32 s16, s16, s21
	s_add_i32 s22, s20, 1
	s_sub_i32 s21, s16, s18
	s_cmp_ge_u32 s16, s18
	s_cselect_b32 s20, s22, s20
	s_cselect_b32 s16, s21, s16
	s_add_i32 s21, s20, 1
	s_cmp_ge_u32 s16, s18
	s_cselect_b32 s16, s21, s20
	s_xor_b32 s16, s16, s19
	s_sub_i32 s16, s16, s19
	s_and_b32 s17, s17, 7
	s_and_b64 s[18:19], s[2:3], exec
	s_mul_hi_i32 s19, s0, 0x38e38e39
	s_cselect_b32 s17, s17, 0
	s_lshr_b32 s20, s19, 31
	s_ashr_i32 s19, s19, 3
	s_add_i32 s19, s19, s20
	s_mul_i32 s20, s19, 36
	s_lshl_b32 s18, s5, 7
	s_sub_i32 s20, s0, s20
	s_and_b64 s[2:3], s[2:3], exec
	s_cselect_b32 s2, 1, 4
	s_lshl_b32 s17, s17, s2
	s_lshl_b32 s2, s20, 5
	s_addk_i32 s2, 0x4000
	v_or_b32_e32 v2, s2, v1
	v_lshlrev_b32_e32 v4, 3, v99
	v_lshlrev_b64 v[2:3], 11, v[2:3]
	v_ashrrev_i32_e32 v5, 31, v4
	s_add_i32 s21, s17, s19
	v_lshl_add_u64 v[2:3], s[12:13], 0, v[2:3]
	v_lshlrev_b64 v[100:101], 1, v[4:5]
	s_ashr_i32 s19, s18, 31
	v_lshl_add_u64 v[2:3], v[2:3], 0, v[100:101]
	s_lshl_b64 s[2:3], s[18:19], 1
	v_lshl_add_u64 v[54:55], v[2:3], 0, s[2:3]
	v_lshl_or_b32 v2, s21, 6, v1
	v_ashrrev_i32_e32 v3, 31, v2
	v_lshlrev_b64 v[2:3], 11, v[2:3]
	v_lshl_add_u64 v[2:3], s[14:15], 0, v[2:3]
	v_lshl_add_u64 v[2:3], v[2:3], 0, v[100:101]
	v_add_co_u32_e32 v62, vcc, s29, v54
	v_lshl_add_u64 v[70:71], v[2:3], 0, s[2:3]
	s_nop 0
	v_addc_co_u32_e32 v63, vcc, 0, v55, vcc
	v_add_co_u32_e32 v78, vcc, s29, v70
	v_lshl_add_u64 v[102:103], s[12:13], 0, v[100:101]
	s_nop 0
	v_addc_co_u32_e32 v79, vcc, 0, v71, vcc
	v_add_co_u32_e32 v86, vcc, s50, v70
	v_lshl_add_u64 v[100:101], s[14:15], 0, v[100:101]
	s_nop 0
	v_addc_co_u32_e32 v87, vcc, 0, v71, vcc
	v_add_co_u32_e32 v94, vcc, s51, v70
	v_lshl_add_u64 v[134:135], v[102:103], 0, s[2:3]
	s_nop 0
	v_addc_co_u32_e32 v95, vcc, 0, v71, vcc
	global_load_dwordx4 v[2:5], v[54:55], off
	global_load_dwordx4 v[6:9], v[54:55], off offset:64
	global_load_dwordx4 v[10:13], v[62:63], off
	global_load_dwordx4 v[14:17], v[62:63], off offset:64
	global_load_dwordx4 v[18:21], v[70:71], off
	global_load_dwordx4 v[22:25], v[70:71], off offset:64
	global_load_dwordx4 v[26:29], v[78:79], off
	global_load_dwordx4 v[30:33], v[78:79], off offset:64
	global_load_dwordx4 v[34:37], v[86:87], off
	global_load_dwordx4 v[38:41], v[86:87], off offset:64
	global_load_dwordx4 v[42:45], v[94:95], off
	global_load_dwordx4 v[46:49], v[94:95], off offset:64
	global_load_dwordx4 v[50:53], v[54:55], off offset:128
	s_nop 0
	global_load_dwordx4 v[54:57], v[54:55], off offset:192
	s_nop 0
	global_load_dwordx4 v[58:61], v[62:63], off offset:128
	s_nop 0
	global_load_dwordx4 v[62:65], v[62:63], off offset:192
	s_nop 0
	global_load_dwordx4 v[66:69], v[70:71], off offset:128
	s_nop 0
	global_load_dwordx4 v[70:73], v[70:71], off offset:192
	s_nop 0
	global_load_dwordx4 v[74:77], v[78:79], off offset:128
	s_nop 0
	global_load_dwordx4 v[78:81], v[78:79], off offset:192
	s_nop 0
	global_load_dwordx4 v[82:85], v[86:87], off offset:128
	s_nop 0
	global_load_dwordx4 v[86:89], v[86:87], off offset:192
	s_nop 0
	global_load_dwordx4 v[90:93], v[94:95], off offset:128
	s_nop 0
	global_load_dwordx4 v[94:97], v[94:95], off offset:192
	v_lshl_add_u64 v[136:137], v[100:101], 0, s[2:3]
	v_lshl_add_u32 v99, s5, 2, v99
	s_lshl_b32 s2, s5, 13
	s_add_i32 s2, s4, s2
	v_lshlrev_b32_e32 v102, 8, v99
	v_lshlrev_b32_e32 v103, 4, v1
	s_lshl_b32 s19, s16, 5
	v_lshl_add_u32 v100, v1, 8, s2
	v_and_b32_e32 v101, -16, v98
	v_add3_u32 v145, s4, v102, v103
	v_lshlrev_b32_e32 v98, 2, v98
	s_add_i32 s4, s19, 0x4000
	v_lshlrev_b32_e32 v144, 2, v1
	v_xor_b32_e32 v146, 4, v98
	v_xor_b32_e32 v147, 8, v98
	v_xor_b32_e32 v148, 16, v98
	v_xor_b32_e32 v149, 32, v98
	v_cmp_eq_u32_e64 s[2:3], 0, v1
	v_add_u32_e32 v150, 0x4000, v99
	s_lshl_b32 s18, s0, 5
	v_or_b32_e32 v151, s4, v1
	v_add_u32_e32 v152, v100, v101
	s_branch .LBB0_1024

; #define LAS __attribute__((address_space(3)))
; #define TAIL_PF(ap_, bp_) do { _Pragma("unroll") for (int s_ = 0; s_ < 4; ++s_) { _Pragma("unroll") for (int i = 0; i < 2; ++i) pa[s_][i] = *(const bf16x8*)((ap_) + i * a16 + 32 * s_); \
;         _Pragma("unroll") for (int f = 0; f < 4; ++f) pb[s_][f] = *(const bf16x8*)((bp_) + f * b16 + 32 * s_); } } while (0)
; template <class Epi>
; __device__ __forceinline__ void gemm_tail(LAS unsigned char* lds_in, int wave_in, const Gemm g, const Epi& E) {
;     ...
;     int G = gridDim.x, bid = blockIdx.x; asm volatile("" : "+s"(G)); asm volatile("" : "+s"(bid));
;     const int r = lane & 15, q = lane >> 4;
;     constexpr int NRT = (MREAL - MTAIL0) / 32, NCT = 1024 / 64;
;     const int klen = g.K / 8, kbeg = wid * klen;
;     const int nx = (G % 8 == 0) ? 8 : 1, x = (nx == 8) ? (bid & 7) : 0, j = (nx == 8) ? (bid >> 3) : bid, nj = G / nx;
;     const int ct_per = NCT / nx, ntile = NRT * ct_per;
;     LAS float* red = (LAS float*)lds;
;     const size_t a16 = (size_t)16 * g.lda, b16 = (size_t)16 * g.ldb;
;     bf16x8 pa[4][2], pb[4][4];
;     ...
;     if (j < ntile) { TAIL_PTRS(j, rt0, ct0, row00, col00, ap0, bp0); (void)row00; TAIL_PF(ap0, bp0); }
.LBB0_1284:
	v_mov_b32_e32 v98, v174
	s_mov_b32 s5, s75
	s_mov_b32 s4, s77
	s_mov_b32 s7, s74
	s_mov_b32 s6, s70
	s_and_b32 s0, s7, 7
	s_ashr_i32 s18, s6, 3
	s_cmp_eq_u32 s0, 8
	s_cselect_b64 s[2:3], -1, 0
	s_and_b64 s[0:1], s[2:3], exec
	s_movk_i32 s1, 0x48
	s_cselect_b32 s0, s18, s6
	s_cselect_b32 s1, s1, 0x240
	s_cmp_ge_i32 s0, s1
	s_movk_i32 s48, 0x6000
	s_mov_b32 s49, 0x9000
	s_mov_b32 s24, 0x16000
	s_mov_b32 s25, 0x2c000
	s_mov_b32 s26, 0x42000
	s_cbranch_scc1 .LBB0_1291
	s_and_b64 s[18:19], s[2:3], exec
	s_cselect_b32 s18, 8, 1
	v_cvt_f32_ubyte0_e32 v1, s18
	v_rcp_iflag_f32_e32 v2, v1
	s_sub_i32 s20, 0, s18
	s_ashr_i32 s19, s7, 31
	s_abs_i32 s7, s7
	v_mul_f32_e32 v2, 0x4f7ffffe, v2
	v_cvt_u32_f32_e32 v2, v2
	v_and_b32_e32 v1, 15, v98
	v_ashrrev_i32_e32 v99, 4, v98
	v_lshlrev_b32_e32 v156, 2, v1
	v_readfirstlane_b32 s21, v2
	s_mul_i32 s20, s20, s21
	s_mul_hi_u32 s20, s21, s20
	s_add_i32 s21, s21, s20
	s_mul_hi_u32 s20, s7, s21
	s_mul_i32 s21, s20, s18
	s_sub_i32 s7, s7, s21
	s_add_i32 s22, s20, 1
	s_sub_i32 s21, s7, s18
	s_cmp_ge_u32 s7, s18
	s_cselect_b32 s20, s22, s20
	s_cselect_b32 s7, s21, s7
	s_add_i32 s21, s20, 1
	s_cmp_ge_u32 s7, s18
	s_cselect_b32 s7, s21, s20
	s_xor_b32 s7, s7, s19
	s_sub_i32 s18, s7, s19
	s_and_b32 s19, s6, 7
	s_and_b64 s[6:7], s[2:3], exec
	s_cselect_b32 s7, s19, 0
	s_mul_hi_i32 s19, s0, 0x38e38e39
	s_lshr_b32 s20, s19, 31
	s_ashr_i32 s19, s19, 3
	s_add_i32 s20, s19, s20
	s_mul_i32 s19, s20, 36
	s_sub_i32 s21, s0, s19
	s_and_b64 s[2:3], s[2:3], exec
	s_cselect_b32 s2, 1, 4
	s_lshl_b32 s19, s7, s2
	s_lshl_b32 s2, s21, 5
	s_addk_i32 s2, 0x4000
	v_or_b32_e32 v4, s2, v1
	s_waitcnt lgkmcnt(0)
	v_mov_b64_e32 v[2:3], s[14:15]
	v_mad_u64_u32 v[2:3], s[2:3], v4, s39, v[2:3]
	v_lshlrev_b32_e32 v4, 3, v99
	s_mul_i32 s6, s5, 0x160
	v_ashrrev_i32_e32 v5, 31, v4
	v_lshlrev_b64 v[100:101], 1, v[4:5]
	s_ashr_i32 s7, s6, 31
	s_add_i32 s20, s19, s20
	v_lshl_add_u64 v[2:3], v[2:3], 0, v[100:101]
	s_lshl_b64 s[2:3], s[6:7], 1
	v_lshl_add_u64 v[54:55], v[2:3], 0, s[2:3]
	v_lshl_or_b32 v4, s20, 6, v1
	v_mov_b64_e32 v[2:3], s[16:17]
	v_mad_i64_i32 v[2:3], s[6:7], v4, s39, v[2:3]
	v_lshl_add_u64 v[2:3], v[2:3], 0, v[100:101]
	v_add_co_u32_e32 v62, vcc, s24, v54
	v_lshl_add_u64 v[70:71], v[2:3], 0, s[2:3]
	s_nop 0
	v_addc_co_u32_e32 v63, vcc, 0, v55, vcc
	v_add_co_u32_e32 v78, vcc, s24, v70
	v_lshl_add_u64 v[102:103], s[14:15], 0, v[100:101]
	s_nop 0
	v_addc_co_u32_e32 v79, vcc, 0, v71, vcc
	v_add_co_u32_e32 v86, vcc, s25, v70
	v_lshl_add_u64 v[100:101], s[16:17], 0, v[100:101]
	s_nop 0
	v_addc_co_u32_e32 v87, vcc, 0, v71, vcc
	v_add_co_u32_e32 v94, vcc, s26, v70
	s_lshl_b32 s6, s5, 2
	s_nop 0
	v_addc_co_u32_e32 v95, vcc, 0, v71, vcc
	global_load_dwordx4 v[2:5], v[54:55], off
	global_load_dwordx4 v[6:9], v[54:55], off offset:64
	global_load_dwordx4 v[10:13], v[62:63], off
	global_load_dwordx4 v[14:17], v[62:63], off offset:64
	global_load_dwordx4 v[18:21], v[70:71], off
	global_load_dwordx4 v[22:25], v[70:71], off offset:64
	global_load_dwordx4 v[26:29], v[78:79], off
	global_load_dwordx4 v[30:33], v[78:79], off offset:64
	global_load_dwordx4 v[34:37], v[86:87], off
	global_load_dwordx4 v[38:41], v[86:87], off offset:64
	global_load_dwordx4 v[42:45], v[94:95], off
	global_load_dwordx4 v[46:49], v[94:95], off offset:64
	global_load_dwordx4 v[50:53], v[54:55], off offset:128
	s_nop 0
	global_load_dwordx4 v[54:57], v[54:55], off offset:192
	s_nop 0
	global_load_dwordx4 v[58:61], v[62:63], off offset:128
	s_nop 0
	global_load_dwordx4 v[62:65], v[62:63], off offset:192
	s_nop 0
	global_load_dwordx4 v[66:69], v[70:71], off offset:128
	s_nop 0
	global_load_dwordx4 v[70:73], v[70:71], off offset:192
	s_nop 0
	global_load_dwordx4 v[74:77], v[78:79], off offset:128
	s_nop 0
	global_load_dwordx4 v[78:81], v[78:79], off offset:192
	s_nop 0
	global_load_dwordx4 v[82:85], v[86:87], off offset:128
	s_nop 0
	global_load_dwordx4 v[86:89], v[86:87], off offset:192
	s_nop 0
	global_load_dwordx4 v[90:93], v[94:95], off offset:128
	s_nop 0
	global_load_dwordx4 v[94:97], v[94:95], off offset:192
	v_lshl_add_u64 v[142:143], v[102:103], 0, s[2:3]
	v_lshl_add_u64 v[144:145], v[100:101], 0, s[2:3]
	s_lshl_b32 s2, s5, 13
	v_add_lshl_u32 v102, s6, v99, 8
	v_lshlrev_b32_e32 v103, 4, v1
	s_add_i32 s2, s4, s2
	v_add3_u32 v157, s4, v102, v103
	s_lshl_b32 s4, s0, 5
	v_and_b32_e32 v101, -16, v98
	v_lshlrev_b32_e32 v98, 2, v98
	s_add_i32 s6, s6, s4
	s_addk_i32 s4, 0x4000
	v_lshl_add_u32 v100, v1, 8, s2
	v_xor_b32_e32 v158, 4, v98
	v_xor_b32_e32 v159, 8, v98
	v_xor_b32_e32 v160, 16, v98
	v_xor_b32_e32 v161, 32, v98
	v_add_u32_e32 v98, s6, v99
	s_lshl_b32 s16, s18, 5
	v_or_b32_e32 v163, s4, v1
	s_mov_b32 s20, 0
	v_cmp_eq_u32_e64 s[2:3], 0, v1
	v_add_u32_e32 v162, 0x4000, v98
	v_add_u32_e32 v164, s16, v163
	v_add_u32_e32 v165, v100, v101
	s_branch .LBB0_1287
